# v41 with MFMA snake chains over all 16 accumulators, B-fragment (first operand) major
# speedup vs baseline: 1.0374x; 1.0001x over previous
.LBB0_159:
	s_add_u32 s0, s22, 0xfff80080
	s_addc_u32 s1, s23, -1
	s_add_i32 s51, 0, 0x10000
	s_cmp_eq_u32 s50, 28
	s_cselect_b32 s27, s15, s1
	s_cselect_b32 s26, s46, s0
	v_add_u32_e32 v140, s51, v143
	s_cselect_b32 s25, s13, s49
	s_cselect_b32 s24, s47, s48
	s_add_i32 s0, 0, 0x14000
	ds_read_b128 v[146:149], v140
	ds_read_b128 v[150:153], v140 offset:1024
	ds_read_b128 v[154:157], v140 offset:2048
	ds_read_b128 v[158:161], v140 offset:3072
	v_add_u32_e32 v140, s0, v143
	ds_read_b128 v[162:165], v140
	ds_read_b128 v[166:169], v140 offset:1024
	ds_read_b128 v[170:173], v140 offset:2048
	ds_read_b128 v[174:177], v140 offset:3072
	v_lshl_add_u64 v[140:141], s[22:23], 0, v[136:137]
	s_add_i32 m0, s35, 0xc000
	ds_read_b128 v[178:181], v144
	ds_read_b128 v[182:185], v144 offset:1024
	ds_read_b128 v[192:195], v144 offset:2048
	ds_read_b128 v[196:199], v144 offset:3072
	ds_read_b128 v[200:203], v144 offset:4096
	ds_read_b128 v[204:207], v144 offset:5120
	ds_read_b128 v[208:211], v144 offset:6144
	ds_read_b128 v[212:215], v144 offset:7168
	global_load_lds_dwordx4 v[140:141], off
	v_lshl_add_u64 v[140:141], s[22:23], 0, v[138:139]
	s_add_i32 m0, s35, 0xe000
	s_nop 0
	global_load_lds_dwordx4 v[140:141], off
	s_waitcnt vmcnt(8)
	s_waitcnt lgkmcnt(0)
	s_setprio 1
	s_barrier

	v_mfma_f32_16x16x32_bf16 v[126:129], v[146:149], v[178:181], v[126:129]
	v_mfma_f32_16x16x32_bf16 v[126:129], v[150:153], v[182:185], v[126:129]
	v_mfma_f32_16x16x32_bf16 v[110:113], v[150:153], v[196:199], v[110:113]
	v_mfma_f32_16x16x32_bf16 v[110:113], v[146:149], v[192:195], v[110:113]
	v_mfma_f32_16x16x32_bf16 v[94:97], v[146:149], v[200:203], v[94:97]
	v_mfma_f32_16x16x32_bf16 v[94:97], v[150:153], v[204:207], v[94:97]
	v_mfma_f32_16x16x32_bf16 v[78:81], v[150:153], v[212:215], v[78:81]
	v_mfma_f32_16x16x32_bf16 v[78:81], v[146:149], v[208:211], v[78:81]
	v_mfma_f32_16x16x32_bf16 v[70:73], v[154:157], v[208:211], v[70:73]
	v_mfma_f32_16x16x32_bf16 v[70:73], v[158:161], v[212:215], v[70:73]
	v_mfma_f32_16x16x32_bf16 v[86:89], v[158:161], v[204:207], v[86:89]
	v_mfma_f32_16x16x32_bf16 v[86:89], v[154:157], v[200:203], v[86:89]
	v_mfma_f32_16x16x32_bf16 v[102:105], v[154:157], v[192:195], v[102:105]
	v_mfma_f32_16x16x32_bf16 v[102:105], v[158:161], v[196:199], v[102:105]
	v_mfma_f32_16x16x32_bf16 v[118:121], v[158:161], v[182:185], v[118:121]
	v_mfma_f32_16x16x32_bf16 v[118:121], v[154:157], v[178:181], v[118:121]


	v_mfma_f32_16x16x32_bf16 v[122:125], v[162:165], v[178:181], v[122:125]
	v_mfma_f32_16x16x32_bf16 v[122:125], v[166:169], v[182:185], v[122:125]
	v_mfma_f32_16x16x32_bf16 v[106:109], v[166:169], v[196:199], v[106:109]
	v_mfma_f32_16x16x32_bf16 v[106:109], v[162:165], v[192:195], v[106:109]
	v_mfma_f32_16x16x32_bf16 v[90:93], v[162:165], v[200:203], v[90:93]
	v_mfma_f32_16x16x32_bf16 v[90:93], v[166:169], v[204:207], v[90:93]
	v_mfma_f32_16x16x32_bf16 v[74:77], v[166:169], v[212:215], v[74:77]
	v_mfma_f32_16x16x32_bf16 v[74:77], v[162:165], v[208:211], v[74:77]
	v_mfma_f32_16x16x32_bf16 v[66:69], v[170:173], v[208:211], v[66:69]
	v_mfma_f32_16x16x32_bf16 v[66:69], v[174:177], v[212:215], v[66:69]
	v_mfma_f32_16x16x32_bf16 v[82:85], v[174:177], v[204:207], v[82:85]
	v_mfma_f32_16x16x32_bf16 v[82:85], v[170:173], v[200:203], v[82:85]
	v_mfma_f32_16x16x32_bf16 v[98:101], v[170:173], v[192:195], v[98:101]
	v_mfma_f32_16x16x32_bf16 v[98:101], v[174:177], v[196:199], v[98:101]
	v_mfma_f32_16x16x32_bf16 v[114:117], v[174:177], v[182:185], v[114:117]
	v_mfma_f32_16x16x32_bf16 v[114:117], v[170:173], v[178:181], v[114:117]
	s_barrier
	s_setprio 0
	s_add_i32 s1, s51, s31
	v_lshl_add_u64 v[140:141], s[24:25], 0, v[186:187]
	s_mov_b32 m0, s1
	ds_read_b128 v[178:181], v144 offset:16384
	ds_read_b128 v[182:185], v144 offset:17408
	ds_read_b128 v[192:195], v144 offset:18432
	ds_read_b128 v[196:199], v144 offset:19456
	ds_read_b128 v[200:203], v144 offset:20480
	ds_read_b128 v[204:207], v144 offset:21504
	ds_read_b128 v[208:211], v144 offset:22528
	ds_read_b128 v[212:215], v144 offset:23552
	global_load_lds_dwordx4 v[140:141], off
	s_add_i32 m0, s1, 0x2000
	s_add_u32 s52, s24, 0x80000
	v_lshl_add_u64 v[216:217], s[24:25], 0, v[130:131]
	s_addc_u32 s53, s25, 0
	s_add_i32 s0, s0, s31
	global_load_lds_dwordx4 v[216:217], off
	v_lshl_add_u64 v[218:219], s[52:53], 0, v[186:187]
	s_mov_b32 m0, s0
	v_lshl_add_u64 v[220:221], s[26:27], 0, v[132:133]
	global_load_lds_dwordx4 v[218:219], off
	v_lshl_add_u64 v[218:219], s[52:53], 0, v[130:131]
	s_add_i32 m0, s0, 0x2000
	s_nop 0
	global_load_lds_dwordx4 v[218:219], off
	v_lshl_add_u64 v[218:219], s[26:27], 0, v[134:135]
	s_mov_b32 m0, s35
	s_nop 0
	global_load_lds_dwordx4 v[218:219], off
	s_mov_b32 m0, s36
	s_nop 0
	global_load_lds_dwordx4 v[220:221], off
	s_waitcnt vmcnt(8)
	s_waitcnt lgkmcnt(0)
	s_setprio 1
	s_barrier

	v_mfma_f32_16x16x32_bf16 v[62:65], v[146:149], v[178:181], v[62:65]
	v_mfma_f32_16x16x32_bf16 v[62:65], v[150:153], v[182:185], v[62:65]
	v_mfma_f32_16x16x32_bf16 v[46:49], v[150:153], v[196:199], v[46:49]
	v_mfma_f32_16x16x32_bf16 v[46:49], v[146:149], v[192:195], v[46:49]
	v_mfma_f32_16x16x32_bf16 v[30:33], v[146:149], v[200:203], v[30:33]
	v_mfma_f32_16x16x32_bf16 v[30:33], v[150:153], v[204:207], v[30:33]
	v_mfma_f32_16x16x32_bf16 v[14:17], v[150:153], v[212:215], v[14:17]
	v_mfma_f32_16x16x32_bf16 v[14:17], v[146:149], v[208:211], v[14:17]
	v_mfma_f32_16x16x32_bf16 v[6:9], v[154:157], v[208:211], v[6:9]
	v_mfma_f32_16x16x32_bf16 v[6:9], v[158:161], v[212:215], v[6:9]
	v_mfma_f32_16x16x32_bf16 v[22:25], v[158:161], v[204:207], v[22:25]
	v_mfma_f32_16x16x32_bf16 v[22:25], v[154:157], v[200:203], v[22:25]
	v_mfma_f32_16x16x32_bf16 v[38:41], v[154:157], v[192:195], v[38:41]
	v_mfma_f32_16x16x32_bf16 v[38:41], v[158:161], v[196:199], v[38:41]
	v_mfma_f32_16x16x32_bf16 v[54:57], v[158:161], v[182:185], v[54:57]
	v_mfma_f32_16x16x32_bf16 v[54:57], v[154:157], v[178:181], v[54:57]


	v_mfma_f32_16x16x32_bf16 v[58:61], v[162:165], v[178:181], v[58:61]
	v_mfma_f32_16x16x32_bf16 v[58:61], v[166:169], v[182:185], v[58:61]
	v_mfma_f32_16x16x32_bf16 v[42:45], v[166:169], v[196:199], v[42:45]
	v_mfma_f32_16x16x32_bf16 v[42:45], v[162:165], v[192:195], v[42:45]
	v_mfma_f32_16x16x32_bf16 v[26:29], v[162:165], v[200:203], v[26:29]
	v_mfma_f32_16x16x32_bf16 v[26:29], v[166:169], v[204:207], v[26:29]
	v_mfma_f32_16x16x32_bf16 v[10:13], v[166:169], v[212:215], v[10:13]
	v_mfma_f32_16x16x32_bf16 v[10:13], v[162:165], v[208:211], v[10:13]
	v_mfma_f32_16x16x32_bf16 v[2:5], v[170:173], v[208:211], v[2:5]
	v_mfma_f32_16x16x32_bf16 v[2:5], v[174:177], v[212:215], v[2:5]
	v_mfma_f32_16x16x32_bf16 v[18:21], v[174:177], v[204:207], v[18:21]
	v_mfma_f32_16x16x32_bf16 v[18:21], v[170:173], v[200:203], v[18:21]
	v_mfma_f32_16x16x32_bf16 v[34:37], v[170:173], v[192:195], v[34:37]
	v_mfma_f32_16x16x32_bf16 v[34:37], v[174:177], v[196:199], v[34:37]
	v_mfma_f32_16x16x32_bf16 v[50:53], v[174:177], v[182:185], v[50:53]
	v_mfma_f32_16x16x32_bf16 v[50:53], v[170:173], v[178:181], v[50:53]
	s_barrier
	s_setprio 0
	s_add_i32 s0, 0, 0x18000
	v_add_u32_e32 v145, s0, v143
	s_add_i32 s1, 0, 0x1c000
	ds_read_b128 v[146:149], v145
	ds_read_b128 v[150:153], v145 offset:1024
	ds_read_b128 v[154:157], v145 offset:2048
	ds_read_b128 v[158:161], v145 offset:3072
	v_add_u32_e32 v145, s1, v143
	ds_read_b128 v[162:165], v145
	ds_read_b128 v[166:169], v145 offset:1024
	ds_read_b128 v[170:173], v145 offset:2048
	ds_read_b128 v[174:177], v145 offset:3072
	s_add_u32 s26, s26, 0x80000
	s_addc_u32 s27, s27, 0
	s_mov_b32 m0, s37
	v_lshl_add_u64 v[222:223], s[26:27], 0, v[134:135]
	ds_read_b128 v[178:181], v144 offset:32768
	ds_read_b128 v[182:185], v144 offset:33792
	ds_read_b128 v[192:195], v144 offset:34816
	ds_read_b128 v[196:199], v144 offset:35840
	ds_read_b128 v[200:203], v144 offset:36864
	ds_read_b128 v[204:207], v144 offset:37888
	ds_read_b128 v[208:211], v144 offset:38912
	ds_read_b128 v[212:215], v144 offset:39936
	global_load_lds_dwordx4 v[222:223], off
	v_lshl_add_u64 v[222:223], s[26:27], 0, v[132:133]
	s_mov_b32 m0, s38
	s_nop 0
	global_load_lds_dwordx4 v[222:223], off
	s_waitcnt vmcnt(8)
	s_waitcnt lgkmcnt(0)
	s_setprio 1
	s_barrier

	v_mfma_f32_16x16x32_bf16 v[126:129], v[146:149], v[178:181], v[126:129]
	v_mfma_f32_16x16x32_bf16 v[126:129], v[150:153], v[182:185], v[126:129]
	v_mfma_f32_16x16x32_bf16 v[110:113], v[150:153], v[196:199], v[110:113]
	v_mfma_f32_16x16x32_bf16 v[110:113], v[146:149], v[192:195], v[110:113]
	v_mfma_f32_16x16x32_bf16 v[94:97], v[146:149], v[200:203], v[94:97]
	v_mfma_f32_16x16x32_bf16 v[94:97], v[150:153], v[204:207], v[94:97]
	v_mfma_f32_16x16x32_bf16 v[78:81], v[150:153], v[212:215], v[78:81]
	v_mfma_f32_16x16x32_bf16 v[78:81], v[146:149], v[208:211], v[78:81]
	v_mfma_f32_16x16x32_bf16 v[70:73], v[154:157], v[208:211], v[70:73]
	v_mfma_f32_16x16x32_bf16 v[70:73], v[158:161], v[212:215], v[70:73]
	v_mfma_f32_16x16x32_bf16 v[86:89], v[158:161], v[204:207], v[86:89]
	v_mfma_f32_16x16x32_bf16 v[86:89], v[154:157], v[200:203], v[86:89]
	v_mfma_f32_16x16x32_bf16 v[102:105], v[154:157], v[192:195], v[102:105]
	v_mfma_f32_16x16x32_bf16 v[102:105], v[158:161], v[196:199], v[102:105]
	v_mfma_f32_16x16x32_bf16 v[118:121], v[158:161], v[182:185], v[118:121]
	v_mfma_f32_16x16x32_bf16 v[118:121], v[154:157], v[178:181], v[118:121]


	v_mfma_f32_16x16x32_bf16 v[122:125], v[162:165], v[178:181], v[122:125]
	v_mfma_f32_16x16x32_bf16 v[122:125], v[166:169], v[182:185], v[122:125]
	v_mfma_f32_16x16x32_bf16 v[106:109], v[166:169], v[196:199], v[106:109]
	v_mfma_f32_16x16x32_bf16 v[106:109], v[162:165], v[192:195], v[106:109]
	v_mfma_f32_16x16x32_bf16 v[90:93], v[162:165], v[200:203], v[90:93]
	v_mfma_f32_16x16x32_bf16 v[90:93], v[166:169], v[204:207], v[90:93]
	v_mfma_f32_16x16x32_bf16 v[74:77], v[166:169], v[212:215], v[74:77]
	v_mfma_f32_16x16x32_bf16 v[74:77], v[162:165], v[208:211], v[74:77]
	v_mfma_f32_16x16x32_bf16 v[66:69], v[170:173], v[208:211], v[66:69]
	v_mfma_f32_16x16x32_bf16 v[66:69], v[174:177], v[212:215], v[66:69]
	v_mfma_f32_16x16x32_bf16 v[82:85], v[174:177], v[204:207], v[82:85]
	v_mfma_f32_16x16x32_bf16 v[82:85], v[170:173], v[200:203], v[82:85]
	v_mfma_f32_16x16x32_bf16 v[98:101], v[170:173], v[192:195], v[98:101]
	v_mfma_f32_16x16x32_bf16 v[98:101], v[174:177], v[196:199], v[98:101]
	v_mfma_f32_16x16x32_bf16 v[114:117], v[174:177], v[182:185], v[114:117]
	v_mfma_f32_16x16x32_bf16 v[114:117], v[170:173], v[178:181], v[114:117]
	s_barrier
	s_setprio 0
	s_add_i32 s0, s0, s31
	v_lshl_add_u64 v[140:141], v[140:141], 0, s[84:85]
	s_mov_b32 m0, s0
	ds_read_b128 v[178:181], v144 offset:49152
	ds_read_b128 v[182:185], v144 offset:50176
	ds_read_b128 v[192:195], v144 offset:51200
	ds_read_b128 v[196:199], v144 offset:52224
	ds_read_b128 v[200:203], v144 offset:53248
	ds_read_b128 v[204:207], v144 offset:54272
	ds_read_b128 v[208:211], v144 offset:55296
	ds_read_b128 v[212:215], v144 offset:56320
	global_load_lds_dwordx4 v[140:141], off
	s_add_i32 m0, s0, 0x2000
	s_add_u32 s24, s24, 0x80080
	v_lshl_add_u64 v[140:141], v[216:217], 0, s[84:85]
	s_addc_u32 s25, s25, 0
	s_add_i32 s0, s1, s31
	global_load_lds_dwordx4 v[140:141], off
	v_lshl_add_u64 v[140:141], s[24:25], 0, v[186:187]
	s_mov_b32 m0, s0
	s_nop 0
	global_load_lds_dwordx4 v[140:141], off
	v_lshl_add_u64 v[140:141], s[24:25], 0, v[130:131]
	s_add_i32 m0, s0, 0x2000
	s_nop 0
	global_load_lds_dwordx4 v[140:141], off
	v_lshl_add_u64 v[140:141], v[218:219], 0, s[84:85]
	s_mov_b32 m0, s39
	s_nop 0
	global_load_lds_dwordx4 v[140:141], off
	v_lshl_add_u64 v[140:141], v[220:221], 0, s[84:85]
	s_mov_b32 m0, s40
	s_nop 0
	global_load_lds_dwordx4 v[140:141], off
	s_waitcnt vmcnt(8)
	s_waitcnt lgkmcnt(0)
	s_setprio 1
	s_barrier

	v_mfma_f32_16x16x32_bf16 v[62:65], v[146:149], v[178:181], v[62:65]
	v_mfma_f32_16x16x32_bf16 v[62:65], v[150:153], v[182:185], v[62:65]
	v_mfma_f32_16x16x32_bf16 v[46:49], v[150:153], v[196:199], v[46:49]
	v_mfma_f32_16x16x32_bf16 v[46:49], v[146:149], v[192:195], v[46:49]
	v_mfma_f32_16x16x32_bf16 v[30:33], v[146:149], v[200:203], v[30:33]
	v_mfma_f32_16x16x32_bf16 v[30:33], v[150:153], v[204:207], v[30:33]
	v_mfma_f32_16x16x32_bf16 v[14:17], v[150:153], v[212:215], v[14:17]
	v_mfma_f32_16x16x32_bf16 v[14:17], v[146:149], v[208:211], v[14:17]
	v_mfma_f32_16x16x32_bf16 v[6:9], v[154:157], v[208:211], v[6:9]
	v_mfma_f32_16x16x32_bf16 v[6:9], v[158:161], v[212:215], v[6:9]
	v_mfma_f32_16x16x32_bf16 v[22:25], v[158:161], v[204:207], v[22:25]
	v_mfma_f32_16x16x32_bf16 v[22:25], v[154:157], v[200:203], v[22:25]
	v_mfma_f32_16x16x32_bf16 v[38:41], v[154:157], v[192:195], v[38:41]
	v_mfma_f32_16x16x32_bf16 v[38:41], v[158:161], v[196:199], v[38:41]
	v_mfma_f32_16x16x32_bf16 v[54:57], v[158:161], v[182:185], v[54:57]
	v_mfma_f32_16x16x32_bf16 v[54:57], v[154:157], v[178:181], v[54:57]


	v_mfma_f32_16x16x32_bf16 v[58:61], v[162:165], v[178:181], v[58:61]
	v_mfma_f32_16x16x32_bf16 v[58:61], v[166:169], v[182:185], v[58:61]
	v_mfma_f32_16x16x32_bf16 v[42:45], v[166:169], v[196:199], v[42:45]
	v_mfma_f32_16x16x32_bf16 v[42:45], v[162:165], v[192:195], v[42:45]
	v_mfma_f32_16x16x32_bf16 v[26:29], v[162:165], v[200:203], v[26:29]
	v_mfma_f32_16x16x32_bf16 v[26:29], v[166:169], v[204:207], v[26:29]
	v_mfma_f32_16x16x32_bf16 v[10:13], v[166:169], v[212:215], v[10:13]
	v_mfma_f32_16x16x32_bf16 v[10:13], v[162:165], v[208:211], v[10:13]
	v_mfma_f32_16x16x32_bf16 v[2:5], v[170:173], v[208:211], v[2:5]
	v_mfma_f32_16x16x32_bf16 v[2:5], v[174:177], v[212:215], v[2:5]
	v_mfma_f32_16x16x32_bf16 v[18:21], v[174:177], v[204:207], v[18:21]
	v_mfma_f32_16x16x32_bf16 v[18:21], v[170:173], v[200:203], v[18:21]
	v_mfma_f32_16x16x32_bf16 v[34:37], v[170:173], v[192:195], v[34:37]
	v_mfma_f32_16x16x32_bf16 v[34:37], v[174:177], v[196:199], v[34:37]
	v_mfma_f32_16x16x32_bf16 v[50:53], v[174:177], v[182:185], v[50:53]
	v_mfma_f32_16x16x32_bf16 v[50:53], v[170:173], v[178:181], v[50:53]
	s_barrier
	s_setprio 0
	s_add_i32 s50, s50, 2
	s_add_u32 s22, s22, 0x100
	s_addc_u32 s23, s23, 0
	s_add_u32 s48, s48, 0x100
	s_addc_u32 s49, s49, 0
	s_cmp_gt_u32 s50, 29
	s_cbranch_scc0 .LBB0_159
	s_and_b64 vcc, exec, s[10:11]
	s_cbranch_vccz .LBB0_162
	s_barrier

.LBB0_243:
	s_add_u32 s22, s20, 0x100
	s_addc_u32 s23, s21, 0
	s_add_i32 s0, 0, 0x10000
	s_cmpk_eq_i32 s51, 0x54
	s_cselect_b32 s27, s7, s23
	s_cselect_b32 s26, s6, s22
	s_cselect_b32 s25, s19, s50
	s_cselect_b32 s24, s18, s49
	s_add_i32 s1, 0, 0x14000
	v_add_u32_e32 v126, s0, v237
	v_add_u32_e32 v158, s1, v237
	ds_read_b128 v[90:93], v126
	ds_read_b128 v[102:105], v126 offset:1024
	ds_read_b128 v[114:117], v126 offset:2048
	ds_read_b128 v[126:129], v126 offset:3072
	ds_read_b128 v[138:141], v158
	ds_read_b128 v[142:145], v158 offset:1024
	ds_read_b128 v[154:157], v158 offset:2048
	ds_read_b128 v[158:161], v158 offset:3072
	v_lshl_add_u64 v[210:211], s[20:21], 0, v[198:199]
	s_add_i32 m0, s34, 0xc000
	ds_read_b128 v[162:165], v238
	ds_read_b128 v[166:169], v238 offset:1024
	ds_read_b128 v[170:173], v238 offset:2048
	ds_read_b128 v[174:177], v238 offset:3072
	ds_read_b128 v[178:181], v238 offset:4096
	ds_read_b128 v[182:185], v238 offset:5120
	ds_read_b128 v[202:205], v238 offset:6144
	ds_read_b128 v[206:209], v238 offset:7168
	global_load_lds_dwordx4 v[210:211], off
	v_lshl_add_u64 v[210:211], s[20:21], 0, v[200:201]
	s_add_i32 m0, s34, 0xe000
	s_nop 0
	global_load_lds_dwordx4 v[210:211], off
	s_waitcnt vmcnt(8)
	s_waitcnt lgkmcnt(0)
	s_setprio 1
	s_barrier

	v_mfma_f32_16x16x32_bf16 v[150:153], v[90:93], v[162:165], v[150:153]
	v_mfma_f32_16x16x32_bf16 v[150:153], v[102:105], v[166:169], v[150:153]
	v_mfma_f32_16x16x32_bf16 v[122:125], v[102:105], v[174:177], v[122:125]
	v_mfma_f32_16x16x32_bf16 v[122:125], v[90:93], v[170:173], v[122:125]
	v_mfma_f32_16x16x32_bf16 v[98:101], v[90:93], v[178:181], v[98:101]
	v_mfma_f32_16x16x32_bf16 v[98:101], v[102:105], v[182:185], v[98:101]
	v_mfma_f32_16x16x32_bf16 v[78:81], v[102:105], v[206:209], v[78:81]
	v_mfma_f32_16x16x32_bf16 v[78:81], v[90:93], v[202:205], v[78:81]
	v_mfma_f32_16x16x32_bf16 v[74:77], v[114:117], v[202:205], v[74:77]
	v_mfma_f32_16x16x32_bf16 v[74:77], v[126:129], v[206:209], v[74:77]
	v_mfma_f32_16x16x32_bf16 v[94:97], v[126:129], v[182:185], v[94:97]
	v_mfma_f32_16x16x32_bf16 v[94:97], v[114:117], v[178:181], v[94:97]
	v_mfma_f32_16x16x32_bf16 v[118:121], v[114:117], v[170:173], v[118:121]
	v_mfma_f32_16x16x32_bf16 v[118:121], v[126:129], v[174:177], v[118:121]
	v_mfma_f32_16x16x32_bf16 v[146:149], v[126:129], v[166:169], v[146:149]
	v_mfma_f32_16x16x32_bf16 v[146:149], v[114:117], v[162:165], v[146:149]


	v_mfma_f32_16x16x32_bf16 v[134:137], v[138:141], v[162:165], v[134:137]
	v_mfma_f32_16x16x32_bf16 v[134:137], v[142:145], v[166:169], v[134:137]
	v_mfma_f32_16x16x32_bf16 v[110:113], v[142:145], v[174:177], v[110:113]
	v_mfma_f32_16x16x32_bf16 v[110:113], v[138:141], v[170:173], v[110:113]
	v_mfma_f32_16x16x32_bf16 v[86:89], v[138:141], v[178:181], v[86:89]
	v_mfma_f32_16x16x32_bf16 v[86:89], v[142:145], v[182:185], v[86:89]
	v_mfma_f32_16x16x32_bf16 v[70:73], v[142:145], v[206:209], v[70:73]
	v_mfma_f32_16x16x32_bf16 v[70:73], v[138:141], v[202:205], v[70:73]
	v_mfma_f32_16x16x32_bf16 v[66:69], v[154:157], v[202:205], v[66:69]
	v_mfma_f32_16x16x32_bf16 v[66:69], v[158:161], v[206:209], v[66:69]
	v_mfma_f32_16x16x32_bf16 v[82:85], v[158:161], v[182:185], v[82:85]
	v_mfma_f32_16x16x32_bf16 v[82:85], v[154:157], v[178:181], v[82:85]
	v_mfma_f32_16x16x32_bf16 v[106:109], v[154:157], v[170:173], v[106:109]
	v_mfma_f32_16x16x32_bf16 v[106:109], v[158:161], v[174:177], v[106:109]
	v_mfma_f32_16x16x32_bf16 v[130:133], v[158:161], v[166:169], v[130:133]
	v_mfma_f32_16x16x32_bf16 v[130:133], v[154:157], v[162:165], v[130:133]
	s_barrier
	s_setprio 0
	s_add_i32 s0, s0, s31
	v_lshl_add_u64 v[210:211], s[24:25], 0, v[186:187]
	s_mov_b32 m0, s0
	ds_read_b128 v[162:165], v238 offset:16384
	ds_read_b128 v[166:169], v238 offset:17408
	ds_read_b128 v[170:173], v238 offset:18432
	ds_read_b128 v[174:177], v238 offset:19456
	ds_read_b128 v[178:181], v238 offset:20480
	ds_read_b128 v[182:185], v238 offset:21504
	ds_read_b128 v[202:205], v238 offset:22528
	ds_read_b128 v[206:209], v238 offset:23552
	global_load_lds_dwordx4 v[210:211], off
	s_add_i32 m0, s0, 0x2000
	s_add_u32 s20, s24, 0x160000
	v_lshl_add_u64 v[212:213], s[24:25], 0, v[196:197]
	s_addc_u32 s21, s25, 0
	s_add_i32 s0, s1, s31
	global_load_lds_dwordx4 v[212:213], off
	v_lshl_add_u64 v[214:215], s[20:21], 0, v[186:187]
	s_mov_b32 m0, s0
	v_lshl_add_u64 v[216:217], s[26:27], 0, v[194:195]
	global_load_lds_dwordx4 v[214:215], off
	v_lshl_add_u64 v[214:215], s[20:21], 0, v[196:197]
	s_add_i32 m0, s0, 0x2000
	s_nop 0
	global_load_lds_dwordx4 v[214:215], off
	v_lshl_add_u64 v[214:215], s[26:27], 0, v[192:193]
	s_mov_b32 m0, s34
	s_nop 0
	global_load_lds_dwordx4 v[214:215], off
	s_mov_b32 m0, s35
	s_nop 0
	global_load_lds_dwordx4 v[216:217], off
	s_waitcnt vmcnt(8)
	s_waitcnt lgkmcnt(0)
	s_setprio 1
	s_barrier

	v_mfma_f32_16x16x32_bf16 v[62:65], v[90:93], v[162:165], v[62:65]
	v_mfma_f32_16x16x32_bf16 v[62:65], v[102:105], v[166:169], v[62:65]
	v_mfma_f32_16x16x32_bf16 v[46:49], v[102:105], v[174:177], v[46:49]
	v_mfma_f32_16x16x32_bf16 v[46:49], v[90:93], v[170:173], v[46:49]
	v_mfma_f32_16x16x32_bf16 v[30:33], v[90:93], v[178:181], v[30:33]
	v_mfma_f32_16x16x32_bf16 v[30:33], v[102:105], v[182:185], v[30:33]
	v_mfma_f32_16x16x32_bf16 v[14:17], v[102:105], v[206:209], v[14:17]
	v_mfma_f32_16x16x32_bf16 v[14:17], v[90:93], v[202:205], v[14:17]
	v_mfma_f32_16x16x32_bf16 v[10:13], v[114:117], v[202:205], v[10:13]
	v_mfma_f32_16x16x32_bf16 v[10:13], v[126:129], v[206:209], v[10:13]
	v_mfma_f32_16x16x32_bf16 v[26:29], v[126:129], v[182:185], v[26:29]
	v_mfma_f32_16x16x32_bf16 v[26:29], v[114:117], v[178:181], v[26:29]
	v_mfma_f32_16x16x32_bf16 v[42:45], v[114:117], v[170:173], v[42:45]
	v_mfma_f32_16x16x32_bf16 v[42:45], v[126:129], v[174:177], v[42:45]
	v_mfma_f32_16x16x32_bf16 v[58:61], v[126:129], v[166:169], v[58:61]
	v_mfma_f32_16x16x32_bf16 v[58:61], v[114:117], v[162:165], v[58:61]


	v_mfma_f32_16x16x32_bf16 v[54:57], v[138:141], v[162:165], v[54:57]
	v_mfma_f32_16x16x32_bf16 v[54:57], v[142:145], v[166:169], v[54:57]
	v_mfma_f32_16x16x32_bf16 v[38:41], v[142:145], v[174:177], v[38:41]
	v_mfma_f32_16x16x32_bf16 v[38:41], v[138:141], v[170:173], v[38:41]
	v_mfma_f32_16x16x32_bf16 v[22:25], v[138:141], v[178:181], v[22:25]
	v_mfma_f32_16x16x32_bf16 v[22:25], v[142:145], v[182:185], v[22:25]
	v_mfma_f32_16x16x32_bf16 v[6:9], v[142:145], v[206:209], v[6:9]
	v_mfma_f32_16x16x32_bf16 v[6:9], v[138:141], v[202:205], v[6:9]
	v_mfma_f32_16x16x32_bf16 v[2:5], v[154:157], v[202:205], v[2:5]
	v_mfma_f32_16x16x32_bf16 v[2:5], v[158:161], v[206:209], v[2:5]
	v_mfma_f32_16x16x32_bf16 v[18:21], v[158:161], v[182:185], v[18:21]
	v_mfma_f32_16x16x32_bf16 v[18:21], v[154:157], v[178:181], v[18:21]
	v_mfma_f32_16x16x32_bf16 v[34:37], v[154:157], v[170:173], v[34:37]
	v_mfma_f32_16x16x32_bf16 v[34:37], v[158:161], v[174:177], v[34:37]
	v_mfma_f32_16x16x32_bf16 v[50:53], v[158:161], v[166:169], v[50:53]
	v_mfma_f32_16x16x32_bf16 v[50:53], v[154:157], v[162:165], v[50:53]
	s_barrier
	s_setprio 0
	s_add_i32 s0, 0, 0x18000
	s_add_i32 s1, 0, 0x1c000
	v_add_u32_e32 v126, s0, v237
	v_add_u32_e32 v158, s1, v237
	ds_read_b128 v[90:93], v126
	ds_read_b128 v[102:105], v126 offset:1024
	ds_read_b128 v[114:117], v126 offset:2048
	ds_read_b128 v[126:129], v126 offset:3072
	ds_read_b128 v[138:141], v158
	ds_read_b128 v[142:145], v158 offset:1024
	ds_read_b128 v[154:157], v158 offset:2048
	ds_read_b128 v[158:161], v158 offset:3072
	s_add_u32 s20, s26, 0x160000
	s_addc_u32 s21, s27, 0
	s_mov_b32 m0, s36
	v_lshl_add_u64 v[218:219], s[20:21], 0, v[192:193]
	ds_read_b128 v[162:165], v238 offset:32768
	ds_read_b128 v[166:169], v238 offset:33792
	ds_read_b128 v[170:173], v238 offset:34816
	ds_read_b128 v[174:177], v238 offset:35840
	ds_read_b128 v[178:181], v238 offset:36864
	ds_read_b128 v[182:185], v238 offset:37888
	ds_read_b128 v[202:205], v238 offset:38912
	ds_read_b128 v[206:209], v238 offset:39936
	global_load_lds_dwordx4 v[218:219], off
	v_lshl_add_u64 v[218:219], s[20:21], 0, v[194:195]
	s_mov_b32 m0, s37
	s_nop 0
	global_load_lds_dwordx4 v[218:219], off
	s_waitcnt vmcnt(8)
	s_waitcnt lgkmcnt(0)
	s_setprio 1
	s_barrier

	v_mfma_f32_16x16x32_bf16 v[150:153], v[90:93], v[162:165], v[150:153]
	v_mfma_f32_16x16x32_bf16 v[150:153], v[102:105], v[166:169], v[150:153]
	v_mfma_f32_16x16x32_bf16 v[122:125], v[102:105], v[174:177], v[122:125]
	v_mfma_f32_16x16x32_bf16 v[122:125], v[90:93], v[170:173], v[122:125]
	v_mfma_f32_16x16x32_bf16 v[98:101], v[90:93], v[178:181], v[98:101]
	v_mfma_f32_16x16x32_bf16 v[98:101], v[102:105], v[182:185], v[98:101]
	v_mfma_f32_16x16x32_bf16 v[78:81], v[102:105], v[206:209], v[78:81]
	v_mfma_f32_16x16x32_bf16 v[78:81], v[90:93], v[202:205], v[78:81]
	v_mfma_f32_16x16x32_bf16 v[74:77], v[114:117], v[202:205], v[74:77]
	v_mfma_f32_16x16x32_bf16 v[74:77], v[126:129], v[206:209], v[74:77]
	v_mfma_f32_16x16x32_bf16 v[94:97], v[126:129], v[182:185], v[94:97]
	v_mfma_f32_16x16x32_bf16 v[94:97], v[114:117], v[178:181], v[94:97]
	v_mfma_f32_16x16x32_bf16 v[118:121], v[114:117], v[170:173], v[118:121]
	v_mfma_f32_16x16x32_bf16 v[118:121], v[126:129], v[174:177], v[118:121]
	v_mfma_f32_16x16x32_bf16 v[146:149], v[126:129], v[166:169], v[146:149]
	v_mfma_f32_16x16x32_bf16 v[146:149], v[114:117], v[162:165], v[146:149]


	v_mfma_f32_16x16x32_bf16 v[134:137], v[138:141], v[162:165], v[134:137]
	v_mfma_f32_16x16x32_bf16 v[134:137], v[142:145], v[166:169], v[134:137]
	v_mfma_f32_16x16x32_bf16 v[110:113], v[142:145], v[174:177], v[110:113]
	v_mfma_f32_16x16x32_bf16 v[110:113], v[138:141], v[170:173], v[110:113]
	v_mfma_f32_16x16x32_bf16 v[86:89], v[138:141], v[178:181], v[86:89]
	v_mfma_f32_16x16x32_bf16 v[86:89], v[142:145], v[182:185], v[86:89]
	v_mfma_f32_16x16x32_bf16 v[70:73], v[142:145], v[206:209], v[70:73]
	v_mfma_f32_16x16x32_bf16 v[70:73], v[138:141], v[202:205], v[70:73]
	v_mfma_f32_16x16x32_bf16 v[66:69], v[154:157], v[202:205], v[66:69]
	v_mfma_f32_16x16x32_bf16 v[66:69], v[158:161], v[206:209], v[66:69]
	v_mfma_f32_16x16x32_bf16 v[82:85], v[158:161], v[182:185], v[82:85]
	v_mfma_f32_16x16x32_bf16 v[82:85], v[154:157], v[178:181], v[82:85]
	v_mfma_f32_16x16x32_bf16 v[106:109], v[154:157], v[170:173], v[106:109]
	v_mfma_f32_16x16x32_bf16 v[106:109], v[158:161], v[174:177], v[106:109]
	v_mfma_f32_16x16x32_bf16 v[130:133], v[158:161], v[166:169], v[130:133]
	v_mfma_f32_16x16x32_bf16 v[130:133], v[154:157], v[162:165], v[130:133]
	s_barrier
	s_setprio 0
	s_add_i32 s0, s0, s31
	v_lshl_add_u64 v[210:211], v[210:211], 0, s[84:85]
	s_mov_b32 m0, s0
	ds_read_b128 v[162:165], v238 offset:49152
	ds_read_b128 v[166:169], v238 offset:50176
	ds_read_b128 v[170:173], v238 offset:51200
	ds_read_b128 v[174:177], v238 offset:52224
	ds_read_b128 v[178:181], v238 offset:53248
	ds_read_b128 v[182:185], v238 offset:54272
	ds_read_b128 v[202:205], v238 offset:55296
	ds_read_b128 v[206:209], v238 offset:56320
	global_load_lds_dwordx4 v[210:211], off
	s_add_i32 m0, s0, 0x2000
	s_add_u32 s20, s24, 0x160080
	v_lshl_add_u64 v[210:211], v[212:213], 0, s[84:85]
	s_addc_u32 s21, s25, 0
	s_add_i32 s0, s1, s31
	global_load_lds_dwordx4 v[210:211], off
	v_lshl_add_u64 v[210:211], s[20:21], 0, v[186:187]
	s_mov_b32 m0, s0
	s_nop 0
	global_load_lds_dwordx4 v[210:211], off
	v_lshl_add_u64 v[210:211], s[20:21], 0, v[196:197]
	s_add_i32 m0, s0, 0x2000
	s_nop 0
	global_load_lds_dwordx4 v[210:211], off
	v_lshl_add_u64 v[210:211], v[214:215], 0, s[84:85]
	s_mov_b32 m0, s41
	s_nop 0
	global_load_lds_dwordx4 v[210:211], off
	v_lshl_add_u64 v[210:211], v[216:217], 0, s[84:85]
	s_mov_b32 m0, s42
	s_nop 0
	global_load_lds_dwordx4 v[210:211], off
	s_waitcnt vmcnt(8)
	s_waitcnt lgkmcnt(0)
	s_setprio 1
	s_barrier

	v_mfma_f32_16x16x32_bf16 v[62:65], v[90:93], v[162:165], v[62:65]
	v_mfma_f32_16x16x32_bf16 v[62:65], v[102:105], v[166:169], v[62:65]
	v_mfma_f32_16x16x32_bf16 v[46:49], v[102:105], v[174:177], v[46:49]
	v_mfma_f32_16x16x32_bf16 v[46:49], v[90:93], v[170:173], v[46:49]
	v_mfma_f32_16x16x32_bf16 v[30:33], v[90:93], v[178:181], v[30:33]
	v_mfma_f32_16x16x32_bf16 v[30:33], v[102:105], v[182:185], v[30:33]
	v_mfma_f32_16x16x32_bf16 v[14:17], v[102:105], v[206:209], v[14:17]
	v_mfma_f32_16x16x32_bf16 v[14:17], v[90:93], v[202:205], v[14:17]
	v_mfma_f32_16x16x32_bf16 v[10:13], v[114:117], v[202:205], v[10:13]
	v_mfma_f32_16x16x32_bf16 v[10:13], v[126:129], v[206:209], v[10:13]
	v_mfma_f32_16x16x32_bf16 v[26:29], v[126:129], v[182:185], v[26:29]
	v_mfma_f32_16x16x32_bf16 v[26:29], v[114:117], v[178:181], v[26:29]
	v_mfma_f32_16x16x32_bf16 v[42:45], v[114:117], v[170:173], v[42:45]
	v_mfma_f32_16x16x32_bf16 v[42:45], v[126:129], v[174:177], v[42:45]
	v_mfma_f32_16x16x32_bf16 v[58:61], v[126:129], v[166:169], v[58:61]
	v_mfma_f32_16x16x32_bf16 v[58:61], v[114:117], v[162:165], v[58:61]


	v_mfma_f32_16x16x32_bf16 v[54:57], v[138:141], v[162:165], v[54:57]
	v_mfma_f32_16x16x32_bf16 v[54:57], v[142:145], v[166:169], v[54:57]
	v_mfma_f32_16x16x32_bf16 v[38:41], v[142:145], v[174:177], v[38:41]
	v_mfma_f32_16x16x32_bf16 v[38:41], v[138:141], v[170:173], v[38:41]
	v_mfma_f32_16x16x32_bf16 v[22:25], v[138:141], v[178:181], v[22:25]
	v_mfma_f32_16x16x32_bf16 v[22:25], v[142:145], v[182:185], v[22:25]
	v_mfma_f32_16x16x32_bf16 v[6:9], v[142:145], v[206:209], v[6:9]
	v_mfma_f32_16x16x32_bf16 v[6:9], v[138:141], v[202:205], v[6:9]
	v_mfma_f32_16x16x32_bf16 v[2:5], v[154:157], v[202:205], v[2:5]
	v_mfma_f32_16x16x32_bf16 v[2:5], v[158:161], v[206:209], v[2:5]
	v_mfma_f32_16x16x32_bf16 v[18:21], v[158:161], v[182:185], v[18:21]
	v_mfma_f32_16x16x32_bf16 v[18:21], v[154:157], v[178:181], v[18:21]
	v_mfma_f32_16x16x32_bf16 v[34:37], v[154:157], v[170:173], v[34:37]
	v_mfma_f32_16x16x32_bf16 v[34:37], v[158:161], v[174:177], v[34:37]
	v_mfma_f32_16x16x32_bf16 v[50:53], v[158:161], v[166:169], v[50:53]
	v_mfma_f32_16x16x32_bf16 v[50:53], v[154:157], v[162:165], v[50:53]
	s_barrier
	s_setprio 0
	s_add_i32 s51, s51, 2
	s_add_u32 s49, s49, 0x100
	s_addc_u32 s50, s50, 0
	s_cmpk_gt_u32 s51, 0x55
	s_mov_b64 s[20:21], s[22:23]
	s_cbranch_scc0 .LBB0_243
	s_and_b64 vcc, exec, s[16:17]
	s_cbranch_vccz .LBB0_246
	s_barrier

.LBB0_443:
	s_add_u32 s0, s26, 0xfff80080
	s_addc_u32 s1, s27, -1
	s_add_i32 s56, 0, 0x10000
	s_cmp_eq_u32 s55, 28
	s_cselect_b32 s31, s19, s1
	s_cselect_b32 s30, s51, s0
	v_add_u32_e32 v140, s56, v144
	s_cselect_b32 s29, s17, s54
	s_cselect_b32 s28, s52, s53
	s_add_i32 s0, 0, 0x14000
	ds_read_b128 v[146:149], v140
	ds_read_b128 v[150:153], v140 offset:1024
	ds_read_b128 v[154:157], v140 offset:2048
	ds_read_b128 v[158:161], v140 offset:3072
	v_add_u32_e32 v140, s0, v144
	ds_read_b128 v[162:165], v140
	ds_read_b128 v[166:169], v140 offset:1024
	ds_read_b128 v[170:173], v140 offset:2048
	ds_read_b128 v[174:177], v140 offset:3072
	v_lshl_add_u64 v[140:141], s[26:27], 0, v[136:137]
	s_add_i32 m0, s25, 0xc000
	ds_read_b128 v[178:181], v145
	ds_read_b128 v[182:185], v145 offset:1024
	ds_read_b128 v[192:195], v145 offset:2048
	ds_read_b128 v[196:199], v145 offset:3072
	ds_read_b128 v[200:203], v145 offset:4096
	ds_read_b128 v[204:207], v145 offset:5120
	ds_read_b128 v[208:211], v145 offset:6144
	ds_read_b128 v[212:215], v145 offset:7168
	global_load_lds_dwordx4 v[140:141], off
	v_lshl_add_u64 v[140:141], s[26:27], 0, v[138:139]
	s_add_i32 m0, s25, 0xe000
	s_nop 0
	global_load_lds_dwordx4 v[140:141], off
	s_waitcnt vmcnt(8)
	s_waitcnt lgkmcnt(0)
	s_setprio 1
	s_barrier

	v_mfma_f32_16x16x32_bf16 v[126:129], v[146:149], v[178:181], v[126:129]
	v_mfma_f32_16x16x32_bf16 v[126:129], v[150:153], v[182:185], v[126:129]
	v_mfma_f32_16x16x32_bf16 v[114:117], v[150:153], v[196:199], v[114:117]
	v_mfma_f32_16x16x32_bf16 v[114:117], v[146:149], v[192:195], v[114:117]
	v_mfma_f32_16x16x32_bf16 v[98:101], v[146:149], v[200:203], v[98:101]
	v_mfma_f32_16x16x32_bf16 v[98:101], v[150:153], v[204:207], v[98:101]
	v_mfma_f32_16x16x32_bf16 v[82:85], v[150:153], v[212:215], v[82:85]
	v_mfma_f32_16x16x32_bf16 v[82:85], v[146:149], v[208:211], v[82:85]
	v_mfma_f32_16x16x32_bf16 v[74:77], v[154:157], v[208:211], v[74:77]
	v_mfma_f32_16x16x32_bf16 v[74:77], v[158:161], v[212:215], v[74:77]
	v_mfma_f32_16x16x32_bf16 v[90:93], v[158:161], v[204:207], v[90:93]
	v_mfma_f32_16x16x32_bf16 v[90:93], v[154:157], v[200:203], v[90:93]
	v_mfma_f32_16x16x32_bf16 v[106:109], v[154:157], v[192:195], v[106:109]
	v_mfma_f32_16x16x32_bf16 v[106:109], v[158:161], v[196:199], v[106:109]
	v_mfma_f32_16x16x32_bf16 v[122:125], v[158:161], v[182:185], v[122:125]
	v_mfma_f32_16x16x32_bf16 v[122:125], v[154:157], v[178:181], v[122:125]


	v_mfma_f32_16x16x32_bf16 v[118:121], v[162:165], v[178:181], v[118:121]
	v_mfma_f32_16x16x32_bf16 v[118:121], v[166:169], v[182:185], v[118:121]
	v_mfma_f32_16x16x32_bf16 v[102:105], v[166:169], v[196:199], v[102:105]
	v_mfma_f32_16x16x32_bf16 v[102:105], v[162:165], v[192:195], v[102:105]
	v_mfma_f32_16x16x32_bf16 v[86:89], v[162:165], v[200:203], v[86:89]
	v_mfma_f32_16x16x32_bf16 v[86:89], v[166:169], v[204:207], v[86:89]
	v_mfma_f32_16x16x32_bf16 v[70:73], v[166:169], v[212:215], v[70:73]
	v_mfma_f32_16x16x32_bf16 v[70:73], v[162:165], v[208:211], v[70:73]
	v_mfma_f32_16x16x32_bf16 v[66:69], v[170:173], v[208:211], v[66:69]
	v_mfma_f32_16x16x32_bf16 v[66:69], v[174:177], v[212:215], v[66:69]
	v_mfma_f32_16x16x32_bf16 v[78:81], v[174:177], v[204:207], v[78:81]
	v_mfma_f32_16x16x32_bf16 v[78:81], v[170:173], v[200:203], v[78:81]
	v_mfma_f32_16x16x32_bf16 v[94:97], v[170:173], v[192:195], v[94:97]
	v_mfma_f32_16x16x32_bf16 v[94:97], v[174:177], v[196:199], v[94:97]
	v_mfma_f32_16x16x32_bf16 v[110:113], v[174:177], v[182:185], v[110:113]
	v_mfma_f32_16x16x32_bf16 v[110:113], v[170:173], v[178:181], v[110:113]
	s_barrier
	s_setprio 0
	s_add_i32 s1, s56, s39
	v_lshl_add_u64 v[140:141], s[28:29], 0, v[186:187]
	s_mov_b32 m0, s1
	ds_read_b128 v[178:181], v145 offset:16384
	ds_read_b128 v[182:185], v145 offset:17408
	ds_read_b128 v[192:195], v145 offset:18432
	ds_read_b128 v[196:199], v145 offset:19456
	ds_read_b128 v[200:203], v145 offset:20480
	ds_read_b128 v[204:207], v145 offset:21504
	ds_read_b128 v[208:211], v145 offset:22528
	ds_read_b128 v[212:215], v145 offset:23552
	global_load_lds_dwordx4 v[140:141], off
	s_add_i32 m0, s1, 0x2000
	s_add_u32 s56, s28, 0x80000
	v_lshl_add_u64 v[188:189], s[28:29], 0, v[130:131]
	s_addc_u32 s57, s29, 0
	s_add_i32 s0, s0, s39
	global_load_lds_dwordx4 v[188:189], off
	v_lshl_add_u64 v[216:217], s[56:57], 0, v[186:187]
	s_mov_b32 m0, s0
	v_lshl_add_u64 v[218:219], s[30:31], 0, v[132:133]
	global_load_lds_dwordx4 v[216:217], off
	v_lshl_add_u64 v[216:217], s[56:57], 0, v[130:131]
	s_add_i32 m0, s0, 0x2000
	s_nop 0
	global_load_lds_dwordx4 v[216:217], off
	v_lshl_add_u64 v[216:217], s[30:31], 0, v[134:135]
	s_mov_b32 m0, s25
	s_nop 0
	global_load_lds_dwordx4 v[216:217], off
	s_mov_b32 m0, s40
	s_nop 0
	global_load_lds_dwordx4 v[218:219], off
	s_waitcnt vmcnt(8)
	s_waitcnt lgkmcnt(0)
	s_setprio 1
	s_barrier

	v_mfma_f32_16x16x32_bf16 v[62:65], v[146:149], v[178:181], v[62:65]
	v_mfma_f32_16x16x32_bf16 v[62:65], v[150:153], v[182:185], v[62:65]
	v_mfma_f32_16x16x32_bf16 v[50:53], v[150:153], v[196:199], v[50:53]
	v_mfma_f32_16x16x32_bf16 v[50:53], v[146:149], v[192:195], v[50:53]
	v_mfma_f32_16x16x32_bf16 v[34:37], v[146:149], v[200:203], v[34:37]
	v_mfma_f32_16x16x32_bf16 v[34:37], v[150:153], v[204:207], v[34:37]
	v_mfma_f32_16x16x32_bf16 v[18:21], v[150:153], v[212:215], v[18:21]
	v_mfma_f32_16x16x32_bf16 v[18:21], v[146:149], v[208:211], v[18:21]
	v_mfma_f32_16x16x32_bf16 v[10:13], v[154:157], v[208:211], v[10:13]
	v_mfma_f32_16x16x32_bf16 v[10:13], v[158:161], v[212:215], v[10:13]
	v_mfma_f32_16x16x32_bf16 v[26:29], v[158:161], v[204:207], v[26:29]
	v_mfma_f32_16x16x32_bf16 v[26:29], v[154:157], v[200:203], v[26:29]
	v_mfma_f32_16x16x32_bf16 v[42:45], v[154:157], v[192:195], v[42:45]
	v_mfma_f32_16x16x32_bf16 v[42:45], v[158:161], v[196:199], v[42:45]
	v_mfma_f32_16x16x32_bf16 v[58:61], v[158:161], v[182:185], v[58:61]
	v_mfma_f32_16x16x32_bf16 v[58:61], v[154:157], v[178:181], v[58:61]


	v_mfma_f32_16x16x32_bf16 v[54:57], v[162:165], v[178:181], v[54:57]
	v_mfma_f32_16x16x32_bf16 v[54:57], v[166:169], v[182:185], v[54:57]
	v_mfma_f32_16x16x32_bf16 v[38:41], v[166:169], v[196:199], v[38:41]
	v_mfma_f32_16x16x32_bf16 v[38:41], v[162:165], v[192:195], v[38:41]
	v_mfma_f32_16x16x32_bf16 v[22:25], v[162:165], v[200:203], v[22:25]
	v_mfma_f32_16x16x32_bf16 v[22:25], v[166:169], v[204:207], v[22:25]
	v_mfma_f32_16x16x32_bf16 v[6:9], v[166:169], v[212:215], v[6:9]
	v_mfma_f32_16x16x32_bf16 v[6:9], v[162:165], v[208:211], v[6:9]
	v_mfma_f32_16x16x32_bf16 v[2:5], v[170:173], v[208:211], v[2:5]
	v_mfma_f32_16x16x32_bf16 v[2:5], v[174:177], v[212:215], v[2:5]
	v_mfma_f32_16x16x32_bf16 v[14:17], v[174:177], v[204:207], v[14:17]
	v_mfma_f32_16x16x32_bf16 v[14:17], v[170:173], v[200:203], v[14:17]
	v_mfma_f32_16x16x32_bf16 v[30:33], v[170:173], v[192:195], v[30:33]
	v_mfma_f32_16x16x32_bf16 v[30:33], v[174:177], v[196:199], v[30:33]
	v_mfma_f32_16x16x32_bf16 v[46:49], v[174:177], v[182:185], v[46:49]
	v_mfma_f32_16x16x32_bf16 v[46:49], v[170:173], v[178:181], v[46:49]
	s_barrier
	s_setprio 0
	s_add_i32 s0, 0, 0x18000
	s_add_i32 s1, 0, 0x1c000
	v_add_u32_e32 v158, s0, v144
	v_add_u32_e32 v174, s1, v144
	ds_read_b128 v[146:149], v158
	ds_read_b128 v[150:153], v158 offset:1024
	ds_read_b128 v[154:157], v158 offset:2048
	ds_read_b128 v[158:161], v158 offset:3072
	ds_read_b128 v[162:165], v174
	ds_read_b128 v[166:169], v174 offset:1024
	ds_read_b128 v[170:173], v174 offset:2048
	ds_read_b128 v[174:177], v174 offset:3072
	s_add_u32 s30, s30, 0x80000
	s_addc_u32 s31, s31, 0
	s_mov_b32 m0, s41
	v_lshl_add_u64 v[220:221], s[30:31], 0, v[134:135]
	ds_read_b128 v[178:181], v145 offset:32768
	ds_read_b128 v[182:185], v145 offset:33792
	ds_read_b128 v[192:195], v145 offset:34816
	ds_read_b128 v[196:199], v145 offset:35840
	ds_read_b128 v[200:203], v145 offset:36864
	ds_read_b128 v[204:207], v145 offset:37888
	ds_read_b128 v[208:211], v145 offset:38912
	ds_read_b128 v[212:215], v145 offset:39936
	global_load_lds_dwordx4 v[220:221], off
	v_lshl_add_u64 v[220:221], s[30:31], 0, v[132:133]
	s_mov_b32 m0, s42
	s_nop 0
	global_load_lds_dwordx4 v[220:221], off
	s_waitcnt vmcnt(8)
	s_waitcnt lgkmcnt(0)
	s_setprio 1
	s_barrier

	v_mfma_f32_16x16x32_bf16 v[126:129], v[146:149], v[178:181], v[126:129]
	v_mfma_f32_16x16x32_bf16 v[126:129], v[150:153], v[182:185], v[126:129]
	v_mfma_f32_16x16x32_bf16 v[114:117], v[150:153], v[196:199], v[114:117]
	v_mfma_f32_16x16x32_bf16 v[114:117], v[146:149], v[192:195], v[114:117]
	v_mfma_f32_16x16x32_bf16 v[98:101], v[146:149], v[200:203], v[98:101]
	v_mfma_f32_16x16x32_bf16 v[98:101], v[150:153], v[204:207], v[98:101]
	v_mfma_f32_16x16x32_bf16 v[82:85], v[150:153], v[212:215], v[82:85]
	v_mfma_f32_16x16x32_bf16 v[82:85], v[146:149], v[208:211], v[82:85]
	v_mfma_f32_16x16x32_bf16 v[74:77], v[154:157], v[208:211], v[74:77]
	v_mfma_f32_16x16x32_bf16 v[74:77], v[158:161], v[212:215], v[74:77]
	v_mfma_f32_16x16x32_bf16 v[90:93], v[158:161], v[204:207], v[90:93]
	v_mfma_f32_16x16x32_bf16 v[90:93], v[154:157], v[200:203], v[90:93]
	v_mfma_f32_16x16x32_bf16 v[106:109], v[154:157], v[192:195], v[106:109]
	v_mfma_f32_16x16x32_bf16 v[106:109], v[158:161], v[196:199], v[106:109]
	v_mfma_f32_16x16x32_bf16 v[122:125], v[158:161], v[182:185], v[122:125]
	v_mfma_f32_16x16x32_bf16 v[122:125], v[154:157], v[178:181], v[122:125]


	v_mfma_f32_16x16x32_bf16 v[118:121], v[162:165], v[178:181], v[118:121]
	v_mfma_f32_16x16x32_bf16 v[118:121], v[166:169], v[182:185], v[118:121]
	v_mfma_f32_16x16x32_bf16 v[102:105], v[166:169], v[196:199], v[102:105]
	v_mfma_f32_16x16x32_bf16 v[102:105], v[162:165], v[192:195], v[102:105]
	v_mfma_f32_16x16x32_bf16 v[86:89], v[162:165], v[200:203], v[86:89]
	v_mfma_f32_16x16x32_bf16 v[86:89], v[166:169], v[204:207], v[86:89]
	v_mfma_f32_16x16x32_bf16 v[70:73], v[166:169], v[212:215], v[70:73]
	v_mfma_f32_16x16x32_bf16 v[70:73], v[162:165], v[208:211], v[70:73]
	v_mfma_f32_16x16x32_bf16 v[66:69], v[170:173], v[208:211], v[66:69]
	v_mfma_f32_16x16x32_bf16 v[66:69], v[174:177], v[212:215], v[66:69]
	v_mfma_f32_16x16x32_bf16 v[78:81], v[174:177], v[204:207], v[78:81]
	v_mfma_f32_16x16x32_bf16 v[78:81], v[170:173], v[200:203], v[78:81]
	v_mfma_f32_16x16x32_bf16 v[94:97], v[170:173], v[192:195], v[94:97]
	v_mfma_f32_16x16x32_bf16 v[94:97], v[174:177], v[196:199], v[94:97]
	v_mfma_f32_16x16x32_bf16 v[110:113], v[174:177], v[182:185], v[110:113]
	v_mfma_f32_16x16x32_bf16 v[110:113], v[170:173], v[178:181], v[110:113]
	s_barrier
	s_setprio 0
	s_add_i32 s0, s0, s39
	v_lshl_add_u64 v[140:141], v[140:141], 0, s[84:85]
	s_mov_b32 m0, s0
	ds_read_b128 v[178:181], v145 offset:49152
	ds_read_b128 v[182:185], v145 offset:50176
	ds_read_b128 v[192:195], v145 offset:51200
	ds_read_b128 v[196:199], v145 offset:52224
	ds_read_b128 v[200:203], v145 offset:53248
	ds_read_b128 v[204:207], v145 offset:54272
	ds_read_b128 v[208:211], v145 offset:55296
	ds_read_b128 v[212:215], v145 offset:56320
	global_load_lds_dwordx4 v[140:141], off
	s_add_i32 m0, s0, 0x2000
	s_add_u32 s28, s28, 0x80080
	v_lshl_add_u64 v[140:141], v[188:189], 0, s[84:85]
	s_addc_u32 s29, s29, 0
	s_add_i32 s0, s1, s39
	global_load_lds_dwordx4 v[140:141], off
	v_lshl_add_u64 v[140:141], s[28:29], 0, v[186:187]
	s_mov_b32 m0, s0
	s_nop 0
	global_load_lds_dwordx4 v[140:141], off
	v_lshl_add_u64 v[140:141], s[28:29], 0, v[130:131]
	s_add_i32 m0, s0, 0x2000
	s_nop 0
	global_load_lds_dwordx4 v[140:141], off
	v_lshl_add_u64 v[140:141], v[216:217], 0, s[84:85]
	s_mov_b32 m0, s43
	s_nop 0
	global_load_lds_dwordx4 v[140:141], off
	v_lshl_add_u64 v[140:141], v[218:219], 0, s[84:85]
	s_mov_b32 m0, s44
	s_nop 0
	global_load_lds_dwordx4 v[140:141], off
	s_waitcnt vmcnt(8)
	s_waitcnt lgkmcnt(0)
	s_setprio 1
	s_barrier

	v_mfma_f32_16x16x32_bf16 v[62:65], v[146:149], v[178:181], v[62:65]
	v_mfma_f32_16x16x32_bf16 v[62:65], v[150:153], v[182:185], v[62:65]
	v_mfma_f32_16x16x32_bf16 v[50:53], v[150:153], v[196:199], v[50:53]
	v_mfma_f32_16x16x32_bf16 v[50:53], v[146:149], v[192:195], v[50:53]
	v_mfma_f32_16x16x32_bf16 v[34:37], v[146:149], v[200:203], v[34:37]
	v_mfma_f32_16x16x32_bf16 v[34:37], v[150:153], v[204:207], v[34:37]
	v_mfma_f32_16x16x32_bf16 v[18:21], v[150:153], v[212:215], v[18:21]
	v_mfma_f32_16x16x32_bf16 v[18:21], v[146:149], v[208:211], v[18:21]
	v_mfma_f32_16x16x32_bf16 v[10:13], v[154:157], v[208:211], v[10:13]
	v_mfma_f32_16x16x32_bf16 v[10:13], v[158:161], v[212:215], v[10:13]
	v_mfma_f32_16x16x32_bf16 v[26:29], v[158:161], v[204:207], v[26:29]
	v_mfma_f32_16x16x32_bf16 v[26:29], v[154:157], v[200:203], v[26:29]
	v_mfma_f32_16x16x32_bf16 v[42:45], v[154:157], v[192:195], v[42:45]
	v_mfma_f32_16x16x32_bf16 v[42:45], v[158:161], v[196:199], v[42:45]
	v_mfma_f32_16x16x32_bf16 v[58:61], v[158:161], v[182:185], v[58:61]
	v_mfma_f32_16x16x32_bf16 v[58:61], v[154:157], v[178:181], v[58:61]


	v_mfma_f32_16x16x32_bf16 v[54:57], v[162:165], v[178:181], v[54:57]
	v_mfma_f32_16x16x32_bf16 v[54:57], v[166:169], v[182:185], v[54:57]
	v_mfma_f32_16x16x32_bf16 v[38:41], v[166:169], v[196:199], v[38:41]
	v_mfma_f32_16x16x32_bf16 v[38:41], v[162:165], v[192:195], v[38:41]
	v_mfma_f32_16x16x32_bf16 v[22:25], v[162:165], v[200:203], v[22:25]
	v_mfma_f32_16x16x32_bf16 v[22:25], v[166:169], v[204:207], v[22:25]
	v_mfma_f32_16x16x32_bf16 v[6:9], v[166:169], v[212:215], v[6:9]
	v_mfma_f32_16x16x32_bf16 v[6:9], v[162:165], v[208:211], v[6:9]
	v_mfma_f32_16x16x32_bf16 v[2:5], v[170:173], v[208:211], v[2:5]
	v_mfma_f32_16x16x32_bf16 v[2:5], v[174:177], v[212:215], v[2:5]
	v_mfma_f32_16x16x32_bf16 v[14:17], v[174:177], v[204:207], v[14:17]
	v_mfma_f32_16x16x32_bf16 v[14:17], v[170:173], v[200:203], v[14:17]
	v_mfma_f32_16x16x32_bf16 v[30:33], v[170:173], v[192:195], v[30:33]
	v_mfma_f32_16x16x32_bf16 v[30:33], v[174:177], v[196:199], v[30:33]
	v_mfma_f32_16x16x32_bf16 v[46:49], v[174:177], v[182:185], v[46:49]
	v_mfma_f32_16x16x32_bf16 v[46:49], v[170:173], v[178:181], v[46:49]
	s_barrier
	s_setprio 0
	s_add_i32 s55, s55, 2
	s_add_u32 s26, s26, 0x100
	s_addc_u32 s27, s27, 0
	s_add_u32 s53, s53, 0x100
	s_addc_u32 s54, s54, 0
	s_cmp_gt_u32 s55, 29
	s_cbranch_scc0 .LBB0_443
	s_and_b64 vcc, exec, s[14:15]
	s_cbranch_vccz .LBB0_446
	s_barrier

.LBB0_1126:
	s_add_u32 s0, s28, 0xfff80080
	s_addc_u32 s1, s29, -1
	s_add_i32 s54, 0, 0x10000
	s_cmp_eq_u32 s53, 28
	s_cselect_b32 s35, s19, s1
	s_cselect_b32 s34, s25, s0
	s_cselect_b32 s31, s17, s52
	s_cselect_b32 s30, s27, s51
	s_add_i32 s55, 0, 0x14000
	v_add_u32_e32 v126, s54, v237
	v_add_u32_e32 v158, s55, v237
	ds_read_b128 v[90:93], v126
	ds_read_b128 v[102:105], v126 offset:1024
	ds_read_b128 v[114:117], v126 offset:2048
	ds_read_b128 v[126:129], v126 offset:3072
	ds_read_b128 v[138:141], v158
	ds_read_b128 v[142:145], v158 offset:1024
	ds_read_b128 v[154:157], v158 offset:2048
	ds_read_b128 v[158:161], v158 offset:3072
	v_lshl_add_u64 v[188:189], s[28:29], 0, v[198:199]
	s_add_i32 m0, s40, 0xc000
	ds_read_b128 v[162:165], v238
	ds_read_b128 v[166:169], v238 offset:1024
	ds_read_b128 v[170:173], v238 offset:2048
	ds_read_b128 v[174:177], v238 offset:3072
	ds_read_b128 v[178:181], v238 offset:4096
	ds_read_b128 v[182:185], v238 offset:5120
	ds_read_b128 v[202:205], v238 offset:6144
	ds_read_b128 v[206:209], v238 offset:7168
	global_load_lds_dwordx4 v[188:189], off
	v_lshl_add_u64 v[188:189], s[28:29], 0, v[200:201]
	s_add_i32 m0, s40, 0xe000
	s_nop 0
	global_load_lds_dwordx4 v[188:189], off
	s_waitcnt vmcnt(8)
	s_waitcnt lgkmcnt(0)
	s_setprio 1
	s_barrier

	v_mfma_f32_16x16x32_bf16 v[150:153], v[90:93], v[162:165], v[150:153]
	v_mfma_f32_16x16x32_bf16 v[150:153], v[102:105], v[166:169], v[150:153]
	v_mfma_f32_16x16x32_bf16 v[122:125], v[102:105], v[174:177], v[122:125]
	v_mfma_f32_16x16x32_bf16 v[122:125], v[90:93], v[170:173], v[122:125]
	v_mfma_f32_16x16x32_bf16 v[98:101], v[90:93], v[178:181], v[98:101]
	v_mfma_f32_16x16x32_bf16 v[98:101], v[102:105], v[182:185], v[98:101]
	v_mfma_f32_16x16x32_bf16 v[78:81], v[102:105], v[206:209], v[78:81]
	v_mfma_f32_16x16x32_bf16 v[78:81], v[90:93], v[202:205], v[78:81]
	v_mfma_f32_16x16x32_bf16 v[74:77], v[114:117], v[202:205], v[74:77]
	v_mfma_f32_16x16x32_bf16 v[74:77], v[126:129], v[206:209], v[74:77]
	v_mfma_f32_16x16x32_bf16 v[94:97], v[126:129], v[182:185], v[94:97]
	v_mfma_f32_16x16x32_bf16 v[94:97], v[114:117], v[178:181], v[94:97]
	v_mfma_f32_16x16x32_bf16 v[118:121], v[114:117], v[170:173], v[118:121]
	v_mfma_f32_16x16x32_bf16 v[118:121], v[126:129], v[174:177], v[118:121]
	v_mfma_f32_16x16x32_bf16 v[146:149], v[126:129], v[166:169], v[146:149]
	v_mfma_f32_16x16x32_bf16 v[146:149], v[114:117], v[162:165], v[146:149]


	v_mfma_f32_16x16x32_bf16 v[134:137], v[138:141], v[162:165], v[134:137]
	v_mfma_f32_16x16x32_bf16 v[134:137], v[142:145], v[166:169], v[134:137]
	v_mfma_f32_16x16x32_bf16 v[110:113], v[142:145], v[174:177], v[110:113]
	v_mfma_f32_16x16x32_bf16 v[110:113], v[138:141], v[170:173], v[110:113]
	v_mfma_f32_16x16x32_bf16 v[86:89], v[138:141], v[178:181], v[86:89]
	v_mfma_f32_16x16x32_bf16 v[86:89], v[142:145], v[182:185], v[86:89]
	v_mfma_f32_16x16x32_bf16 v[70:73], v[142:145], v[206:209], v[70:73]
	v_mfma_f32_16x16x32_bf16 v[70:73], v[138:141], v[202:205], v[70:73]
	v_mfma_f32_16x16x32_bf16 v[66:69], v[154:157], v[202:205], v[66:69]
	v_mfma_f32_16x16x32_bf16 v[66:69], v[158:161], v[206:209], v[66:69]
	v_mfma_f32_16x16x32_bf16 v[82:85], v[158:161], v[182:185], v[82:85]
	v_mfma_f32_16x16x32_bf16 v[82:85], v[154:157], v[178:181], v[82:85]
	v_mfma_f32_16x16x32_bf16 v[106:109], v[154:157], v[170:173], v[106:109]
	v_mfma_f32_16x16x32_bf16 v[106:109], v[158:161], v[174:177], v[106:109]
	v_mfma_f32_16x16x32_bf16 v[130:133], v[158:161], v[166:169], v[130:133]
	v_mfma_f32_16x16x32_bf16 v[130:133], v[154:157], v[162:165], v[130:133]
	s_barrier
	s_setprio 0
	s_add_i32 s0, s54, s39
	v_lshl_add_u64 v[188:189], s[30:31], 0, v[186:187]
	s_mov_b32 m0, s0
	ds_read_b128 v[162:165], v238 offset:16384
	ds_read_b128 v[166:169], v238 offset:17408
	ds_read_b128 v[170:173], v238 offset:18432
	ds_read_b128 v[174:177], v238 offset:19456
	ds_read_b128 v[178:181], v238 offset:20480
	ds_read_b128 v[182:185], v238 offset:21504
	ds_read_b128 v[202:205], v238 offset:22528
	ds_read_b128 v[206:209], v238 offset:23552
	global_load_lds_dwordx4 v[188:189], off
	s_add_i32 m0, s0, 0x2000
	s_add_u32 s0, s30, 0x80000
	v_lshl_add_u64 v[210:211], s[30:31], 0, v[196:197]
	s_addc_u32 s1, s31, 0
	s_add_i32 s54, s55, s39
	global_load_lds_dwordx4 v[210:211], off
	v_lshl_add_u64 v[212:213], s[0:1], 0, v[186:187]
	s_mov_b32 m0, s54
	v_lshl_add_u64 v[214:215], s[34:35], 0, v[194:195]
	global_load_lds_dwordx4 v[212:213], off
	v_lshl_add_u64 v[212:213], s[0:1], 0, v[196:197]
	s_add_i32 m0, s54, 0x2000
	s_nop 0
	global_load_lds_dwordx4 v[212:213], off
	v_lshl_add_u64 v[212:213], s[34:35], 0, v[192:193]
	s_mov_b32 m0, s40
	s_nop 0
	global_load_lds_dwordx4 v[212:213], off
	s_mov_b32 m0, s41
	s_nop 0
	global_load_lds_dwordx4 v[214:215], off
	s_waitcnt vmcnt(8)
	s_waitcnt lgkmcnt(0)
	s_setprio 1
	s_barrier

	v_mfma_f32_16x16x32_bf16 v[62:65], v[90:93], v[162:165], v[62:65]
	v_mfma_f32_16x16x32_bf16 v[62:65], v[102:105], v[166:169], v[62:65]
	v_mfma_f32_16x16x32_bf16 v[46:49], v[102:105], v[174:177], v[46:49]
	v_mfma_f32_16x16x32_bf16 v[46:49], v[90:93], v[170:173], v[46:49]
	v_mfma_f32_16x16x32_bf16 v[30:33], v[90:93], v[178:181], v[30:33]
	v_mfma_f32_16x16x32_bf16 v[30:33], v[102:105], v[182:185], v[30:33]
	v_mfma_f32_16x16x32_bf16 v[14:17], v[102:105], v[206:209], v[14:17]
	v_mfma_f32_16x16x32_bf16 v[14:17], v[90:93], v[202:205], v[14:17]
	v_mfma_f32_16x16x32_bf16 v[10:13], v[114:117], v[202:205], v[10:13]
	v_mfma_f32_16x16x32_bf16 v[10:13], v[126:129], v[206:209], v[10:13]
	v_mfma_f32_16x16x32_bf16 v[26:29], v[126:129], v[182:185], v[26:29]
	v_mfma_f32_16x16x32_bf16 v[26:29], v[114:117], v[178:181], v[26:29]
	v_mfma_f32_16x16x32_bf16 v[42:45], v[114:117], v[170:173], v[42:45]
	v_mfma_f32_16x16x32_bf16 v[42:45], v[126:129], v[174:177], v[42:45]
	v_mfma_f32_16x16x32_bf16 v[58:61], v[126:129], v[166:169], v[58:61]
	v_mfma_f32_16x16x32_bf16 v[58:61], v[114:117], v[162:165], v[58:61]


	v_mfma_f32_16x16x32_bf16 v[54:57], v[138:141], v[162:165], v[54:57]
	v_mfma_f32_16x16x32_bf16 v[54:57], v[142:145], v[166:169], v[54:57]
	v_mfma_f32_16x16x32_bf16 v[38:41], v[142:145], v[174:177], v[38:41]
	v_mfma_f32_16x16x32_bf16 v[38:41], v[138:141], v[170:173], v[38:41]
	v_mfma_f32_16x16x32_bf16 v[22:25], v[138:141], v[178:181], v[22:25]
	v_mfma_f32_16x16x32_bf16 v[22:25], v[142:145], v[182:185], v[22:25]
	v_mfma_f32_16x16x32_bf16 v[6:9], v[142:145], v[206:209], v[6:9]
	v_mfma_f32_16x16x32_bf16 v[6:9], v[138:141], v[202:205], v[6:9]
	v_mfma_f32_16x16x32_bf16 v[2:5], v[154:157], v[202:205], v[2:5]
	v_mfma_f32_16x16x32_bf16 v[2:5], v[158:161], v[206:209], v[2:5]
	v_mfma_f32_16x16x32_bf16 v[18:21], v[158:161], v[182:185], v[18:21]
	v_mfma_f32_16x16x32_bf16 v[18:21], v[154:157], v[178:181], v[18:21]
	v_mfma_f32_16x16x32_bf16 v[34:37], v[154:157], v[170:173], v[34:37]
	v_mfma_f32_16x16x32_bf16 v[34:37], v[158:161], v[174:177], v[34:37]
	v_mfma_f32_16x16x32_bf16 v[50:53], v[158:161], v[166:169], v[50:53]
	v_mfma_f32_16x16x32_bf16 v[50:53], v[154:157], v[162:165], v[50:53]
	s_barrier
	s_setprio 0
	s_add_i32 s54, 0, 0x18000
	s_add_i32 s55, 0, 0x1c000
	v_add_u32_e32 v126, s54, v237
	v_add_u32_e32 v158, s55, v237
	ds_read_b128 v[90:93], v126
	ds_read_b128 v[102:105], v126 offset:1024
	ds_read_b128 v[114:117], v126 offset:2048
	ds_read_b128 v[126:129], v126 offset:3072
	ds_read_b128 v[138:141], v158
	ds_read_b128 v[142:145], v158 offset:1024
	ds_read_b128 v[154:157], v158 offset:2048
	ds_read_b128 v[158:161], v158 offset:3072
	s_add_u32 s0, s34, 0x80000
	s_addc_u32 s1, s35, 0
	s_mov_b32 m0, s42
	v_lshl_add_u64 v[216:217], s[0:1], 0, v[192:193]
	ds_read_b128 v[162:165], v238 offset:32768
	ds_read_b128 v[166:169], v238 offset:33792
	ds_read_b128 v[170:173], v238 offset:34816
	ds_read_b128 v[174:177], v238 offset:35840
	ds_read_b128 v[178:181], v238 offset:36864
	ds_read_b128 v[182:185], v238 offset:37888
	ds_read_b128 v[202:205], v238 offset:38912
	ds_read_b128 v[206:209], v238 offset:39936
	global_load_lds_dwordx4 v[216:217], off
	v_lshl_add_u64 v[216:217], s[0:1], 0, v[194:195]
	s_mov_b32 m0, s43
	s_nop 0
	global_load_lds_dwordx4 v[216:217], off
	s_waitcnt vmcnt(8)
	s_waitcnt lgkmcnt(0)
	s_setprio 1
	s_barrier

	v_mfma_f32_16x16x32_bf16 v[150:153], v[90:93], v[162:165], v[150:153]
	v_mfma_f32_16x16x32_bf16 v[150:153], v[102:105], v[166:169], v[150:153]
	v_mfma_f32_16x16x32_bf16 v[122:125], v[102:105], v[174:177], v[122:125]
	v_mfma_f32_16x16x32_bf16 v[122:125], v[90:93], v[170:173], v[122:125]
	v_mfma_f32_16x16x32_bf16 v[98:101], v[90:93], v[178:181], v[98:101]
	v_mfma_f32_16x16x32_bf16 v[98:101], v[102:105], v[182:185], v[98:101]
	v_mfma_f32_16x16x32_bf16 v[78:81], v[102:105], v[206:209], v[78:81]
	v_mfma_f32_16x16x32_bf16 v[78:81], v[90:93], v[202:205], v[78:81]
	v_mfma_f32_16x16x32_bf16 v[74:77], v[114:117], v[202:205], v[74:77]
	v_mfma_f32_16x16x32_bf16 v[74:77], v[126:129], v[206:209], v[74:77]
	v_mfma_f32_16x16x32_bf16 v[94:97], v[126:129], v[182:185], v[94:97]
	v_mfma_f32_16x16x32_bf16 v[94:97], v[114:117], v[178:181], v[94:97]
	v_mfma_f32_16x16x32_bf16 v[118:121], v[114:117], v[170:173], v[118:121]
	v_mfma_f32_16x16x32_bf16 v[118:121], v[126:129], v[174:177], v[118:121]
	v_mfma_f32_16x16x32_bf16 v[146:149], v[126:129], v[166:169], v[146:149]
	v_mfma_f32_16x16x32_bf16 v[146:149], v[114:117], v[162:165], v[146:149]


	v_mfma_f32_16x16x32_bf16 v[134:137], v[138:141], v[162:165], v[134:137]
	v_mfma_f32_16x16x32_bf16 v[134:137], v[142:145], v[166:169], v[134:137]
	v_mfma_f32_16x16x32_bf16 v[110:113], v[142:145], v[174:177], v[110:113]
	v_mfma_f32_16x16x32_bf16 v[110:113], v[138:141], v[170:173], v[110:113]
	v_mfma_f32_16x16x32_bf16 v[86:89], v[138:141], v[178:181], v[86:89]
	v_mfma_f32_16x16x32_bf16 v[86:89], v[142:145], v[182:185], v[86:89]
	v_mfma_f32_16x16x32_bf16 v[70:73], v[142:145], v[206:209], v[70:73]
	v_mfma_f32_16x16x32_bf16 v[70:73], v[138:141], v[202:205], v[70:73]
	v_mfma_f32_16x16x32_bf16 v[66:69], v[154:157], v[202:205], v[66:69]
	v_mfma_f32_16x16x32_bf16 v[66:69], v[158:161], v[206:209], v[66:69]
	v_mfma_f32_16x16x32_bf16 v[82:85], v[158:161], v[182:185], v[82:85]
	v_mfma_f32_16x16x32_bf16 v[82:85], v[154:157], v[178:181], v[82:85]
	v_mfma_f32_16x16x32_bf16 v[106:109], v[154:157], v[170:173], v[106:109]
	v_mfma_f32_16x16x32_bf16 v[106:109], v[158:161], v[174:177], v[106:109]
	v_mfma_f32_16x16x32_bf16 v[130:133], v[158:161], v[166:169], v[130:133]
	v_mfma_f32_16x16x32_bf16 v[130:133], v[154:157], v[162:165], v[130:133]
	s_barrier
	s_setprio 0
	s_add_i32 s0, s54, s39
	v_lshl_add_u64 v[188:189], v[188:189], 0, s[84:85]
	s_mov_b32 m0, s0
	ds_read_b128 v[162:165], v238 offset:49152
	ds_read_b128 v[166:169], v238 offset:50176
	ds_read_b128 v[170:173], v238 offset:51200
	ds_read_b128 v[174:177], v238 offset:52224
	ds_read_b128 v[178:181], v238 offset:53248
	ds_read_b128 v[182:185], v238 offset:54272
	ds_read_b128 v[202:205], v238 offset:55296
	ds_read_b128 v[206:209], v238 offset:56320
	global_load_lds_dwordx4 v[188:189], off
	s_add_i32 m0, s0, 0x2000
	s_add_u32 s0, s30, 0x80080
	v_lshl_add_u64 v[188:189], v[210:211], 0, s[84:85]
	s_addc_u32 s1, s31, 0
	s_add_i32 s30, s55, s39
	global_load_lds_dwordx4 v[188:189], off
	v_lshl_add_u64 v[188:189], s[0:1], 0, v[186:187]
	s_mov_b32 m0, s30
	s_nop 0
	global_load_lds_dwordx4 v[188:189], off
	v_lshl_add_u64 v[188:189], s[0:1], 0, v[196:197]
	s_add_i32 m0, s30, 0x2000
	s_nop 0
	global_load_lds_dwordx4 v[188:189], off
	v_lshl_add_u64 v[188:189], v[212:213], 0, s[84:85]
	s_mov_b32 m0, s47
	s_nop 0
	global_load_lds_dwordx4 v[188:189], off
	v_lshl_add_u64 v[188:189], v[214:215], 0, s[84:85]
	s_mov_b32 m0, s48
	s_nop 0
	global_load_lds_dwordx4 v[188:189], off
	s_waitcnt vmcnt(8)
	s_waitcnt lgkmcnt(0)
	s_setprio 1
	s_barrier

	v_mfma_f32_16x16x32_bf16 v[62:65], v[90:93], v[162:165], v[62:65]
	v_mfma_f32_16x16x32_bf16 v[62:65], v[102:105], v[166:169], v[62:65]
	v_mfma_f32_16x16x32_bf16 v[46:49], v[102:105], v[174:177], v[46:49]
	v_mfma_f32_16x16x32_bf16 v[46:49], v[90:93], v[170:173], v[46:49]
	v_mfma_f32_16x16x32_bf16 v[30:33], v[90:93], v[178:181], v[30:33]
	v_mfma_f32_16x16x32_bf16 v[30:33], v[102:105], v[182:185], v[30:33]
	v_mfma_f32_16x16x32_bf16 v[14:17], v[102:105], v[206:209], v[14:17]
	v_mfma_f32_16x16x32_bf16 v[14:17], v[90:93], v[202:205], v[14:17]
	v_mfma_f32_16x16x32_bf16 v[10:13], v[114:117], v[202:205], v[10:13]
	v_mfma_f32_16x16x32_bf16 v[10:13], v[126:129], v[206:209], v[10:13]
	v_mfma_f32_16x16x32_bf16 v[26:29], v[126:129], v[182:185], v[26:29]
	v_mfma_f32_16x16x32_bf16 v[26:29], v[114:117], v[178:181], v[26:29]
	v_mfma_f32_16x16x32_bf16 v[42:45], v[114:117], v[170:173], v[42:45]
	v_mfma_f32_16x16x32_bf16 v[42:45], v[126:129], v[174:177], v[42:45]
	v_mfma_f32_16x16x32_bf16 v[58:61], v[126:129], v[166:169], v[58:61]
	v_mfma_f32_16x16x32_bf16 v[58:61], v[114:117], v[162:165], v[58:61]


	v_mfma_f32_16x16x32_bf16 v[54:57], v[138:141], v[162:165], v[54:57]
	v_mfma_f32_16x16x32_bf16 v[54:57], v[142:145], v[166:169], v[54:57]
	v_mfma_f32_16x16x32_bf16 v[38:41], v[142:145], v[174:177], v[38:41]
	v_mfma_f32_16x16x32_bf16 v[38:41], v[138:141], v[170:173], v[38:41]
	v_mfma_f32_16x16x32_bf16 v[22:25], v[138:141], v[178:181], v[22:25]
	v_mfma_f32_16x16x32_bf16 v[22:25], v[142:145], v[182:185], v[22:25]
	v_mfma_f32_16x16x32_bf16 v[6:9], v[142:145], v[206:209], v[6:9]
	v_mfma_f32_16x16x32_bf16 v[6:9], v[138:141], v[202:205], v[6:9]
	v_mfma_f32_16x16x32_bf16 v[2:5], v[154:157], v[202:205], v[2:5]
	v_mfma_f32_16x16x32_bf16 v[2:5], v[158:161], v[206:209], v[2:5]
	v_mfma_f32_16x16x32_bf16 v[18:21], v[158:161], v[182:185], v[18:21]
	v_mfma_f32_16x16x32_bf16 v[18:21], v[154:157], v[178:181], v[18:21]
	v_mfma_f32_16x16x32_bf16 v[34:37], v[154:157], v[170:173], v[34:37]
	v_mfma_f32_16x16x32_bf16 v[34:37], v[158:161], v[174:177], v[34:37]
	v_mfma_f32_16x16x32_bf16 v[50:53], v[158:161], v[166:169], v[50:53]
	v_mfma_f32_16x16x32_bf16 v[50:53], v[154:157], v[162:165], v[50:53]
	s_barrier
	s_setprio 0
	s_add_i32 s53, s53, 2
	s_add_u32 s28, s28, 0x100
	s_addc_u32 s29, s29, 0
	s_add_u32 s51, s51, 0x100
	s_addc_u32 s52, s52, 0
	s_cmp_gt_u32 s53, 29
	s_cbranch_scc0 .LBB0_1126
	s_and_b64 vcc, exec, s[14:15]
	s_cbranch_vccz .LBB0_1129
	s_barrier
